# attention B pass 2 merge: the single vmcnt(0) after the 16 merge loads split per tile (vmcnt(8) before the first tile's math, vmcnt(0) right before the second tile's data is first read)
# speedup vs baseline: 1.0500x; 1.0022x over previous
.LBB0_847:
	s_add_i32 s14, s44, s79
	s_cmp_lg_u32 s85, s14
	s_cbranch_scc1 .LBB0_856
	v_mov_b32_e32 v3, v137
	v_rcp_f32_e32 v108, v50
	s_nop 2
	v_rcp_f32_e32 v104, v46
	s_mov_b64 s[0:1], -1
	v_and_b32_e32 v54, 15, v3
	v_add_u32_e32 v54, s38, v54
	v_and_b32_e32 v110, -16, v3
	v_ashrrev_i32_e32 v111, 31, v110
	s_and_b64 vcc, exec, s[72:73]
	v_add_u32_e32 v106, s92, v54
	v_add_u32_e32 v102, s86, v54
	s_cbranch_vccz .LBB0_850
	v_lshlrev_b32_e32 v60, s90, v106
	v_add_u32_e32 v60, s26, v60
	v_ashrrev_i32_e32 v61, 31, v60
	v_ashrrev_i32_e32 v66, 2, v60
	v_lshlrev_b64 v[62:63], 7, v[60:61]
	v_lshlrev_b32_e32 v64, 11, v60
	v_ashrrev_i32_e32 v67, 31, v66
	v_lshlrev_b64 v[116:117], 11, v[60:61]
	v_lshlrev_b64 v[60:61], 6, v[60:61]
	v_and_b32_e32 v64, 0x1800, v64
	v_mov_b32_e32 v65, v2
	v_lshl_add_u64 v[66:67], s[30:31], 0, v[66:67]
	v_lshl_add_u64 v[60:61], s[66:67], 0, v[60:61]
	v_lshlrev_b64 v[114:115], 1, v[110:111]
	v_lshl_add_u64 v[64:65], v[66:67], 0, v[64:65]
	global_load_dword v107, v[60:61], off nt
	v_add_co_u32_e32 v60, vcc, s49, v60
	v_lshl_add_u64 v[54:55], s[62:63], 0, v[114:115]
	v_lshl_add_u64 v[56:57], s[10:11], 0, v[114:115]
	v_lshl_add_u64 v[58:59], s[64:65], 0, v[114:115]
	v_lshlrev_b64 v[64:65], 7, v[64:65]
	v_addc_co_u32_e32 v61, vcc, 0, v61, vcc
	v_lshl_add_u64 v[62:63], v[54:55], 0, v[62:63]
	v_lshl_add_u64 v[64:65], v[56:57], 0, v[64:65]
	v_lshl_add_u64 v[66:67], v[58:59], 0, v[116:117]
	global_load_dword v109, v[60:61], off nt
	global_load_dwordx4 v[82:85], v[62:63], off offset:16 nt
	global_load_dwordx4 v[94:97], v[62:63], off nt
	global_load_dwordx4 v[86:89], v[64:65], off offset:16 nt
	global_load_dwordx4 v[98:101], v[64:65], off nt
	global_load_dwordx4 v[78:81], v[66:67], off offset:16 nt
	global_load_dwordx4 v[90:93], v[66:67], off nt
	v_log_f32_e32 v118, v50
	v_lshlrev_b32_e32 v60, s90, v102
	v_add_u32_e32 v60, s26, v60
	v_ashrrev_i32_e32 v61, 31, v60
	v_add_f32_e32 v118, v5, v118
	v_lshlrev_b64 v[62:63], 7, v[60:61]
	v_ashrrev_i32_e32 v64, 2, v60
	v_lshl_add_u64 v[54:55], v[54:55], 0, v[62:63]
	v_lshlrev_b32_e32 v62, 11, v60
	v_ashrrev_i32_e32 v65, 31, v64
	v_lshlrev_b64 v[112:113], 11, v[60:61]
	v_and_b32_e32 v62, 0x1800, v62
	v_mov_b32_e32 v63, v2
	v_lshl_add_u64 v[64:65], s[30:31], 0, v[64:65]
	v_lshl_add_u64 v[66:67], v[58:59], 0, v[112:113]
	v_lshlrev_b64 v[58:59], 6, v[60:61]
	v_lshl_add_u64 v[62:63], v[64:65], 0, v[62:63]
	v_lshl_add_u64 v[58:59], s[66:67], 0, v[58:59]
	v_lshlrev_b64 v[62:63], 7, v[62:63]
	global_load_dword v103, v[58:59], off nt
	v_add_co_u32_e32 v58, vcc, s49, v58
	v_lshl_add_u64 v[56:57], v[56:57], 0, v[62:63]
	s_nop 0
	v_addc_co_u32_e32 v59, vcc, 0, v59, vcc
	global_load_dword v105, v[58:59], off nt
	s_nop 0
	global_load_dwordx4 v[58:61], v[54:55], off offset:16 nt
	global_load_dwordx4 v[70:73], v[54:55], off nt
	global_load_dwordx4 v[62:65], v[56:57], off offset:16 nt
	global_load_dwordx4 v[74:77], v[56:57], off nt
	s_nop 0
	global_load_dwordx4 v[54:57], v[66:67], off offset:16 nt
	s_nop 0
	global_load_dwordx4 v[66:69], v[66:67], off nt
	v_lshl_add_u64 v[114:115], s[68:69], 0, v[114:115]
	s_mov_b64 s[0:1], 0
	s_waitcnt vmcnt(8)
	v_max3_f32 v119, v118, v107, v109
	v_sub_f32_e32 v107, v107, v119
	v_exp_f32_e32 v121, v107
	v_sub_f32_e32 v107, v109, v119
	v_exp_f32_e32 v120, v107
	v_sub_f32_e32 v107, v118, v119
	v_lshlrev_b32_e32 v126, 16, v90
	v_and_b32_e32 v127, 0xffff0000, v90
	v_mul_f32_e32 v90, 0xbfb8aa3b, v126
	v_exp_f32_e32 v90, v90
	v_exp_f32_e32 v107, v107
	v_add_f32_e32 v109, v121, v120
	v_lshlrev_b32_e32 v124, 16, v94
	v_add_f32_e32 v90, 1.0, v90
	v_rcp_f32_e32 v128, v90
	v_mul_f32_e32 v90, 0xbfb8aa3b, v127
	v_exp_f32_e32 v90, v90
	v_add_f32_e32 v109, v107, v109
	v_rcp_f32_e32 v122, v109
	v_and_b32_e32 v125, 0xffff0000, v98
	v_add_f32_e32 v90, 1.0, v90
	v_rcp_f32_e32 v129, v90
	v_pk_mul_f32 v[120:121], v[120:121], v[122:123] op_sel_hi:[1,0]
	v_mul_f32_e32 v107, v107, v122
	v_lshlrev_b32_e32 v122, 16, v98
	v_and_b32_e32 v123, 0xffff0000, v94
	v_pk_mul_f32 v[124:125], v[120:121], v[124:125] op_sel:[1,0] op_sel_hi:[0,1]
	v_mul_f32_e32 v118, v108, v107
	v_pk_fma_f32 v[122:123], v[120:121], v[122:123], v[124:125]
	v_pk_mul_f32 v[126:127], v[128:129], v[126:127]
	v_pk_fma_f32 v[122:123], v[42:43], v[118:119], v[122:123] op_sel_hi:[1,0,1]
	v_lshlrev_b32_e32 v98, 16, v91
	v_pk_mul_f32 v[122:123], v[122:123], v[126:127]
	v_lshlrev_b32_e32 v94, 16, v95
	v_cvt_pk_bf16_f32 v90, v122, v123
	v_lshlrev_b32_e32 v122, 16, v99
	v_and_b32_e32 v123, 0xffff0000, v95
	v_and_b32_e32 v95, 0xffff0000, v99
	v_and_b32_e32 v99, 0xffff0000, v91
	v_mul_f32_e32 v91, 0xbfb8aa3b, v98
	v_exp_f32_e32 v91, v91
	v_pk_mul_f32 v[94:95], v[120:121], v[94:95] op_sel:[1,0] op_sel_hi:[0,1]
	v_pk_fma_f32 v[94:95], v[120:121], v[122:123], v[94:95]
	v_lshlrev_b32_e32 v122, 16, v92
	v_add_f32_e32 v91, 1.0, v91
	v_rcp_f32_e32 v124, v91
	v_mul_f32_e32 v91, 0xbfb8aa3b, v99
	v_exp_f32_e32 v91, v91
	v_and_b32_e32 v123, 0xffff0000, v92
	v_mul_f32_e32 v92, 0xbfb8aa3b, v122
	v_exp_f32_e32 v92, v92
	v_add_f32_e32 v91, 1.0, v91
	v_rcp_f32_e32 v125, v91
	v_pk_fma_f32 v[94:95], v[44:45], v[118:119], v[94:95] op_sel_hi:[1,0,1]
	v_add_f32_e32 v92, 1.0, v92
	v_pk_mul_f32 v[98:99], v[124:125], v[98:99]
	s_nop 0
	v_pk_mul_f32 v[94:95], v[94:95], v[98:99]
	v_lshlrev_b32_e32 v98, 16, v96
	v_and_b32_e32 v99, 0xffff0000, v100
	v_cvt_pk_bf16_f32 v91, v94, v95
	v_lshlrev_b32_e32 v94, 16, v100
	v_and_b32_e32 v95, 0xffff0000, v96
	v_pk_mul_f32 v[98:99], v[120:121], v[98:99] op_sel:[1,0] op_sel_hi:[0,1]
	v_pk_fma_f32 v[94:95], v[120:121], v[94:95], v[98:99]
	v_lshlrev_b32_e32 v98, 16, v93
	v_rcp_f32_e32 v124, v92
	v_mul_f32_e32 v92, 0xbfb8aa3b, v123
	v_and_b32_e32 v99, 0xffff0000, v93
	v_mul_f32_e32 v93, 0xbfb8aa3b, v98
	v_exp_f32_e32 v92, v92
	v_exp_f32_e32 v93, v93
	v_pk_fma_f32 v[94:95], v[38:39], v[118:119], v[94:95] op_sel_hi:[1,0,1]
	v_lshlrev_b32_e32 v96, 16, v97
	v_add_f32_e32 v92, 1.0, v92
	v_add_f32_e32 v93, 1.0, v93
	v_rcp_f32_e32 v125, v92
	v_rcp_f32_e32 v100, v93
	v_mul_f32_e32 v93, 0xbfb8aa3b, v99
	v_exp_f32_e32 v93, v93
	v_pk_mul_f32 v[122:123], v[124:125], v[122:123]
	v_add_f32_e32 v93, 1.0, v93
	v_pk_mul_f32 v[94:95], v[94:95], v[122:123]
	s_nop 0
	v_cvt_pk_bf16_f32 v92, v94, v95
	v_lshlrev_b32_e32 v94, 16, v101
	v_and_b32_e32 v95, 0xffff0000, v97
	v_and_b32_e32 v97, 0xffff0000, v101
	v_rcp_f32_e32 v101, v93
	v_pk_mul_f32 v[96:97], v[120:121], v[96:97] op_sel:[1,0] op_sel_hi:[0,1]
	v_pk_fma_f32 v[94:95], v[120:121], v[94:95], v[96:97]
	v_lshlrev_b32_e32 v96, 16, v82
	v_pk_mul_f32 v[98:99], v[100:101], v[98:99]
	v_pk_fma_f32 v[94:95], v[40:41], v[118:119], v[94:95] op_sel_hi:[1,0,1]
	v_and_b32_e32 v97, 0xffff0000, v86
	v_pk_mul_f32 v[94:95], v[94:95], v[98:99]
	v_lshlrev_b32_e32 v98, 16, v78
	v_and_b32_e32 v99, 0xffff0000, v78
	v_mul_f32_e32 v78, 0xbfb8aa3b, v98
	v_exp_f32_e32 v78, v78
	v_cvt_pk_bf16_f32 v93, v94, v95
	v_lshlrev_b32_e32 v94, 16, v86
	v_and_b32_e32 v95, 0xffff0000, v82
	v_add_f32_e32 v78, 1.0, v78
	v_rcp_f32_e32 v100, v78
	v_mul_f32_e32 v78, 0xbfb8aa3b, v99
	v_exp_f32_e32 v78, v78
	v_pk_mul_f32 v[96:97], v[120:121], v[96:97] op_sel:[1,0] op_sel_hi:[0,1]
	v_pk_fma_f32 v[94:95], v[120:121], v[94:95], v[96:97]
	v_lshlrev_b32_e32 v86, 16, v79
	v_add_f32_e32 v78, 1.0, v78
	v_rcp_f32_e32 v101, v78
	v_pk_fma_f32 v[94:95], v[34:35], v[118:119], v[94:95] op_sel_hi:[1,0,1]
	v_lshlrev_b32_e32 v82, 16, v83
	v_pk_mul_f32 v[98:99], v[100:101], v[98:99]
	s_nop 0
	v_pk_mul_f32 v[94:95], v[94:95], v[98:99]
	s_nop 0
	v_cvt_pk_bf16_f32 v78, v94, v95
	v_lshlrev_b32_e32 v94, 16, v87
	v_and_b32_e32 v95, 0xffff0000, v83
	v_and_b32_e32 v83, 0xffff0000, v87
	v_and_b32_e32 v87, 0xffff0000, v79
	v_mul_f32_e32 v79, 0xbfb8aa3b, v86
	v_exp_f32_e32 v79, v79
	v_pk_mul_f32 v[82:83], v[120:121], v[82:83] op_sel:[1,0] op_sel_hi:[0,1]
	v_pk_fma_f32 v[82:83], v[120:121], v[94:95], v[82:83]
	v_add_f32_e32 v79, 1.0, v79
	v_rcp_f32_e32 v96, v79
	v_mul_f32_e32 v79, 0xbfb8aa3b, v87
	v_exp_f32_e32 v79, v79
	v_pk_fma_f32 v[82:83], v[36:37], v[118:119], v[82:83] op_sel_hi:[1,0,1]
	v_add_f32_e32 v79, 1.0, v79
	v_rcp_f32_e32 v97, v79
	s_nop 0
	v_pk_mul_f32 v[86:87], v[96:97], v[86:87]
	s_nop 0
	v_pk_mul_f32 v[82:83], v[82:83], v[86:87]
	v_lshlrev_b32_e32 v86, 16, v85
	v_and_b32_e32 v87, 0xffff0000, v89
	v_cvt_pk_bf16_f32 v79, v82, v83
	v_lshlrev_b32_e32 v82, 16, v89
	v_and_b32_e32 v83, 0xffff0000, v85
	v_pk_mul_f32 v[86:87], v[120:121], v[86:87] op_sel:[1,0] op_sel_hi:[0,1]
	v_pk_fma_f32 v[82:83], v[120:121], v[82:83], v[86:87]
	v_lshlrev_b32_e32 v86, 16, v88
	v_and_b32_e32 v85, 0xffff0000, v88
	v_lshlrev_b32_e32 v88, 16, v80
	v_and_b32_e32 v89, 0xffff0000, v80
	v_mul_f32_e32 v80, 0xbfb8aa3b, v88
	v_exp_f32_e32 v80, v80
	v_and_b32_e32 v87, 0xffff0000, v84
	v_lshlrev_b32_e32 v84, 16, v84
	v_pk_mul_f32 v[84:85], v[120:121], v[84:85] op_sel:[1,0] op_sel_hi:[0,1]
	v_add_f32_e32 v80, 1.0, v80
	v_rcp_f32_e32 v94, v80
	v_mul_f32_e32 v80, 0xbfb8aa3b, v89
	v_exp_f32_e32 v80, v80
	v_pk_fma_f32 v[84:85], v[120:121], v[86:87], v[84:85]
	v_pk_fma_f32 v[82:83], v[32:33], v[118:119], v[82:83] op_sel_hi:[1,0,1]
	v_pk_fma_f32 v[84:85], v[30:31], v[118:119], v[84:85] op_sel_hi:[1,0,1]
	v_add_f32_e32 v80, 1.0, v80
	v_rcp_f32_e32 v95, v80
	s_nop 0
	v_pk_mul_f32 v[88:89], v[94:95], v[88:89]
	s_nop 0
	v_pk_mul_f32 v[84:85], v[84:85], v[88:89]
	s_nop 0
	v_cvt_pk_bf16_f32 v80, v84, v85
	v_lshlrev_b32_e32 v84, 16, v81
	v_and_b32_e32 v85, 0xffff0000, v81
	v_mul_f32_e32 v81, 0xbfb8aa3b, v84
	v_exp_f32_e32 v81, v81
	s_nop 0
	v_add_f32_e32 v81, 1.0, v81
	v_rcp_f32_e32 v86, v81
	v_mul_f32_e32 v81, 0xbfb8aa3b, v85
	v_exp_f32_e32 v81, v81
	s_nop 0
	v_add_f32_e32 v81, 1.0, v81
	v_rcp_f32_e32 v87, v81
	s_nop 0
	v_pk_mul_f32 v[84:85], v[86:87], v[84:85]
	s_nop 0
	v_pk_mul_f32 v[82:83], v[82:83], v[84:85]
	s_waitcnt vmcnt(0)
	v_lshlrev_b32_e32 v86, 16, v66
	v_cvt_pk_bf16_f32 v81, v82, v83
	v_lshl_add_u64 v[82:83], v[114:115], 0, v[116:117]
	global_store_dwordx4 v[82:83], v[90:93], off
	global_store_dwordx4 v[82:83], v[78:81], off offset:16
	v_and_b32_e32 v87, 0xffff0000, v66
	v_mul_f32_e32 v66, 0xbfb8aa3b, v86
	v_log_f32_e32 v78, v46
	v_exp_f32_e32 v66, v66
	v_lshlrev_b32_e32 v84, 16, v70
	v_and_b32_e32 v85, 0xffff0000, v74
	v_add_f32_e32 v78, v4, v78
	v_max3_f32 v79, v78, v103, v105
	v_sub_f32_e32 v80, v103, v79
	v_exp_f32_e32 v81, v80
	v_sub_f32_e32 v80, v105, v79
	v_exp_f32_e32 v80, v80
	v_sub_f32_e32 v78, v78, v79
	v_exp_f32_e32 v78, v78
	v_add_f32_e32 v66, 1.0, v66
	v_rcp_f32_e32 v88, v66
	v_mul_f32_e32 v66, 0xbfb8aa3b, v87
	v_add_f32_e32 v79, v81, v80
	v_exp_f32_e32 v66, v66
	v_add_f32_e32 v79, v78, v79
	v_rcp_f32_e32 v82, v79
	v_add_f32_e32 v66, 1.0, v66
	v_rcp_f32_e32 v89, v66
	v_pk_mul_f32 v[80:81], v[80:81], v[82:83] op_sel_hi:[1,0]
	v_mul_f32_e32 v78, v78, v82
	v_lshlrev_b32_e32 v82, 16, v74
	v_and_b32_e32 v83, 0xffff0000, v70
	v_pk_mul_f32 v[84:85], v[80:81], v[84:85] op_sel:[1,0] op_sel_hi:[0,1]
	v_mul_f32_e32 v78, v104, v78
	v_pk_fma_f32 v[82:83], v[80:81], v[82:83], v[84:85]
	v_pk_mul_f32 v[86:87], v[88:89], v[86:87]
	v_pk_fma_f32 v[82:83], v[26:27], v[78:79], v[82:83] op_sel_hi:[1,0,1]
	v_lshlrev_b32_e32 v74, 16, v67
	v_pk_mul_f32 v[82:83], v[82:83], v[86:87]
	v_lshlrev_b32_e32 v70, 16, v71
	v_cvt_pk_bf16_f32 v66, v82, v83
	v_lshlrev_b32_e32 v82, 16, v75
	v_and_b32_e32 v83, 0xffff0000, v71
	v_and_b32_e32 v71, 0xffff0000, v75
	v_and_b32_e32 v75, 0xffff0000, v67
	v_mul_f32_e32 v67, 0xbfb8aa3b, v74
	v_exp_f32_e32 v67, v67
	v_pk_mul_f32 v[70:71], v[80:81], v[70:71] op_sel:[1,0] op_sel_hi:[0,1]
	v_pk_fma_f32 v[70:71], v[80:81], v[82:83], v[70:71]
	v_lshlrev_b32_e32 v82, 16, v68
	v_add_f32_e32 v67, 1.0, v67
	v_rcp_f32_e32 v84, v67
	v_mul_f32_e32 v67, 0xbfb8aa3b, v75
	v_exp_f32_e32 v67, v67
	v_and_b32_e32 v83, 0xffff0000, v68
	v_mul_f32_e32 v68, 0xbfb8aa3b, v82
	v_exp_f32_e32 v68, v68
	v_add_f32_e32 v67, 1.0, v67
	v_rcp_f32_e32 v85, v67
	v_pk_fma_f32 v[70:71], v[28:29], v[78:79], v[70:71] op_sel_hi:[1,0,1]
	v_add_f32_e32 v68, 1.0, v68
	v_pk_mul_f32 v[74:75], v[84:85], v[74:75]
	s_nop 0
	v_pk_mul_f32 v[70:71], v[70:71], v[74:75]
	v_lshlrev_b32_e32 v74, 16, v72
	v_and_b32_e32 v75, 0xffff0000, v76
	v_cvt_pk_bf16_f32 v67, v70, v71
	v_lshlrev_b32_e32 v70, 16, v76
	v_and_b32_e32 v71, 0xffff0000, v72
	v_pk_mul_f32 v[74:75], v[80:81], v[74:75] op_sel:[1,0] op_sel_hi:[0,1]
	v_pk_fma_f32 v[70:71], v[80:81], v[70:71], v[74:75]
	v_lshlrev_b32_e32 v74, 16, v69
	v_rcp_f32_e32 v84, v68
	v_mul_f32_e32 v68, 0xbfb8aa3b, v83
	v_and_b32_e32 v75, 0xffff0000, v69
	v_mul_f32_e32 v69, 0xbfb8aa3b, v74
	v_exp_f32_e32 v68, v68
	v_exp_f32_e32 v69, v69
	v_pk_fma_f32 v[70:71], v[22:23], v[78:79], v[70:71] op_sel_hi:[1,0,1]
	v_lshlrev_b32_e32 v72, 16, v73
	v_add_f32_e32 v68, 1.0, v68
	v_add_f32_e32 v69, 1.0, v69
	v_rcp_f32_e32 v85, v68
	v_rcp_f32_e32 v76, v69
	v_mul_f32_e32 v69, 0xbfb8aa3b, v75
	v_exp_f32_e32 v69, v69
	v_pk_mul_f32 v[82:83], v[84:85], v[82:83]
	v_add_f32_e32 v69, 1.0, v69
	v_pk_mul_f32 v[70:71], v[70:71], v[82:83]
	s_nop 0
	v_cvt_pk_bf16_f32 v68, v70, v71
	v_lshlrev_b32_e32 v70, 16, v77
	v_and_b32_e32 v71, 0xffff0000, v73
	v_and_b32_e32 v73, 0xffff0000, v77
	v_rcp_f32_e32 v77, v69
	v_pk_mul_f32 v[72:73], v[80:81], v[72:73] op_sel:[1,0] op_sel_hi:[0,1]
	v_pk_fma_f32 v[70:71], v[80:81], v[70:71], v[72:73]
	v_lshlrev_b32_e32 v72, 16, v58
	v_pk_mul_f32 v[74:75], v[76:77], v[74:75]
	v_pk_fma_f32 v[70:71], v[24:25], v[78:79], v[70:71] op_sel_hi:[1,0,1]
	v_and_b32_e32 v73, 0xffff0000, v62
	v_pk_mul_f32 v[70:71], v[70:71], v[74:75]
	v_lshlrev_b32_e32 v74, 16, v54
	v_and_b32_e32 v75, 0xffff0000, v54
	v_mul_f32_e32 v54, 0xbfb8aa3b, v74
	v_exp_f32_e32 v54, v54
	v_cvt_pk_bf16_f32 v69, v70, v71
	v_lshlrev_b32_e32 v70, 16, v62
	v_and_b32_e32 v71, 0xffff0000, v58
	v_add_f32_e32 v54, 1.0, v54
	v_rcp_f32_e32 v76, v54
	v_mul_f32_e32 v54, 0xbfb8aa3b, v75
	v_exp_f32_e32 v54, v54
	v_pk_mul_f32 v[72:73], v[80:81], v[72:73] op_sel:[1,0] op_sel_hi:[0,1]
	v_pk_fma_f32 v[70:71], v[80:81], v[70:71], v[72:73]
	v_lshlrev_b32_e32 v62, 16, v55
	v_add_f32_e32 v54, 1.0, v54
	v_rcp_f32_e32 v77, v54
	v_pk_fma_f32 v[70:71], v[18:19], v[78:79], v[70:71] op_sel_hi:[1,0,1]
	v_lshlrev_b32_e32 v58, 16, v59
	v_pk_mul_f32 v[74:75], v[76:77], v[74:75]
	s_nop 0
	v_pk_mul_f32 v[70:71], v[70:71], v[74:75]
	s_nop 0
	v_cvt_pk_bf16_f32 v54, v70, v71
	v_lshlrev_b32_e32 v70, 16, v63
	v_and_b32_e32 v71, 0xffff0000, v59
	v_and_b32_e32 v59, 0xffff0000, v63
	v_and_b32_e32 v63, 0xffff0000, v55
	v_mul_f32_e32 v55, 0xbfb8aa3b, v62
	v_exp_f32_e32 v55, v55
	v_pk_mul_f32 v[58:59], v[80:81], v[58:59] op_sel:[1,0] op_sel_hi:[0,1]
	v_pk_fma_f32 v[58:59], v[80:81], v[70:71], v[58:59]
	v_add_f32_e32 v55, 1.0, v55
	v_rcp_f32_e32 v72, v55
	v_mul_f32_e32 v55, 0xbfb8aa3b, v63
	v_exp_f32_e32 v55, v55
	v_pk_fma_f32 v[58:59], v[20:21], v[78:79], v[58:59] op_sel_hi:[1,0,1]
	v_add_f32_e32 v55, 1.0, v55
	v_rcp_f32_e32 v73, v55
	s_nop 0
	v_pk_mul_f32 v[62:63], v[72:73], v[62:63]
	s_nop 0
	v_pk_mul_f32 v[58:59], v[58:59], v[62:63]
	v_lshlrev_b32_e32 v62, 16, v61
	v_and_b32_e32 v63, 0xffff0000, v65
	v_cvt_pk_bf16_f32 v55, v58, v59
	v_lshlrev_b32_e32 v58, 16, v65
	v_and_b32_e32 v59, 0xffff0000, v61
	v_pk_mul_f32 v[62:63], v[80:81], v[62:63] op_sel:[1,0] op_sel_hi:[0,1]
	v_pk_fma_f32 v[58:59], v[80:81], v[58:59], v[62:63]
	v_lshlrev_b32_e32 v62, 16, v64
	v_and_b32_e32 v61, 0xffff0000, v64
	v_lshlrev_b32_e32 v64, 16, v56
	v_and_b32_e32 v65, 0xffff0000, v56
	v_mul_f32_e32 v56, 0xbfb8aa3b, v64
	v_exp_f32_e32 v56, v56
	v_and_b32_e32 v63, 0xffff0000, v60
	v_lshlrev_b32_e32 v60, 16, v60
	v_pk_mul_f32 v[60:61], v[80:81], v[60:61] op_sel:[1,0] op_sel_hi:[0,1]
	v_add_f32_e32 v56, 1.0, v56
	v_rcp_f32_e32 v70, v56
	v_mul_f32_e32 v56, 0xbfb8aa3b, v65
	v_exp_f32_e32 v56, v56
	v_pk_fma_f32 v[60:61], v[80:81], v[62:63], v[60:61]
	v_pk_fma_f32 v[58:59], v[16:17], v[78:79], v[58:59] op_sel_hi:[1,0,1]
	v_pk_fma_f32 v[60:61], v[14:15], v[78:79], v[60:61] op_sel_hi:[1,0,1]
	v_add_f32_e32 v56, 1.0, v56
	v_rcp_f32_e32 v71, v56
	s_nop 0
	v_pk_mul_f32 v[64:65], v[70:71], v[64:65]
	s_nop 0
	v_pk_mul_f32 v[60:61], v[60:61], v[64:65]
	s_nop 0
	v_cvt_pk_bf16_f32 v56, v60, v61
	v_lshlrev_b32_e32 v60, 16, v57
	v_and_b32_e32 v61, 0xffff0000, v57
	v_mul_f32_e32 v57, 0xbfb8aa3b, v60
	v_exp_f32_e32 v57, v57
	s_nop 0
	v_add_f32_e32 v57, 1.0, v57
	v_rcp_f32_e32 v62, v57
	v_mul_f32_e32 v57, 0xbfb8aa3b, v61
	v_exp_f32_e32 v57, v57
	s_nop 0
	v_add_f32_e32 v57, 1.0, v57
	v_rcp_f32_e32 v63, v57
	s_nop 0
	v_pk_mul_f32 v[60:61], v[62:63], v[60:61]
	s_nop 0
	v_pk_mul_f32 v[58:59], v[58:59], v[60:61]
	s_nop 0
	v_cvt_pk_bf16_f32 v57, v58, v59
	v_lshl_add_u64 v[58:59], v[114:115], 0, v[112:113]
	global_store_dwordx4 v[58:59], v[66:69], off
	global_store_dwordx4 v[58:59], v[54:57], off offset:16

.LBB0_867:
	s_cmp_lg_u32 s40, s14
	s_cbranch_scc1 .LBB0_827
	v_mov_b32_e32 v3, v137
	v_rcp_f32_e32 v108, v50
	s_nop 3
	v_rcp_f32_e32 v104, v46
	s_mov_b64 s[0:1], -1
	v_and_b32_e32 v54, 15, v3
	v_add_u32_e32 v54, s38, v54
	v_and_b32_e32 v110, -16, v3
	v_ashrrev_i32_e32 v111, 31, v110
	s_andn2_b64 vcc, exec, s[72:73]
	v_add_u32_e32 v106, s19, v54
	v_add_u32_e32 v102, s93, v54
	s_cbranch_vccnz .LBB0_870
	v_lshlrev_b32_e32 v60, s90, v106
	v_add_u32_e32 v60, s26, v60
	v_ashrrev_i32_e32 v61, 31, v60
	v_ashrrev_i32_e32 v66, 2, v60
	v_lshlrev_b64 v[62:63], 7, v[60:61]
	v_lshlrev_b32_e32 v64, 11, v60
	v_ashrrev_i32_e32 v67, 31, v66
	v_lshlrev_b64 v[116:117], 11, v[60:61]
	v_lshlrev_b64 v[60:61], 6, v[60:61]
	v_and_b32_e32 v64, 0x1800, v64
	v_mov_b32_e32 v65, v2
	v_lshl_add_u64 v[66:67], s[30:31], 0, v[66:67]
	v_lshl_add_u64 v[60:61], s[66:67], 0, v[60:61]
	v_lshlrev_b64 v[114:115], 1, v[110:111]
	v_lshl_add_u64 v[64:65], v[66:67], 0, v[64:65]
	global_load_dword v107, v[60:61], off nt
	v_add_co_u32_e32 v60, vcc, s49, v60
	v_lshl_add_u64 v[54:55], s[62:63], 0, v[114:115]
	v_lshl_add_u64 v[56:57], s[10:11], 0, v[114:115]
	v_lshl_add_u64 v[58:59], s[64:65], 0, v[114:115]
	v_lshlrev_b64 v[64:65], 7, v[64:65]
	v_addc_co_u32_e32 v61, vcc, 0, v61, vcc
	v_lshl_add_u64 v[62:63], v[54:55], 0, v[62:63]
	v_lshl_add_u64 v[64:65], v[56:57], 0, v[64:65]
	v_lshl_add_u64 v[66:67], v[58:59], 0, v[116:117]
	global_load_dword v109, v[60:61], off nt
	global_load_dwordx4 v[82:85], v[62:63], off offset:16 nt
	global_load_dwordx4 v[94:97], v[62:63], off nt
	global_load_dwordx4 v[86:89], v[64:65], off offset:16 nt
	global_load_dwordx4 v[98:101], v[64:65], off nt
	global_load_dwordx4 v[78:81], v[66:67], off offset:16 nt
	global_load_dwordx4 v[90:93], v[66:67], off nt
	v_log_f32_e32 v118, v50
	v_lshlrev_b32_e32 v60, s90, v102
	v_add_u32_e32 v60, s26, v60
	v_ashrrev_i32_e32 v61, 31, v60
	v_add_f32_e32 v118, v5, v118
	v_lshlrev_b64 v[62:63], 7, v[60:61]
	v_ashrrev_i32_e32 v64, 2, v60
	v_lshl_add_u64 v[54:55], v[54:55], 0, v[62:63]
	v_lshlrev_b32_e32 v62, 11, v60
	v_ashrrev_i32_e32 v65, 31, v64
	v_lshlrev_b64 v[112:113], 11, v[60:61]
	v_and_b32_e32 v62, 0x1800, v62
	v_mov_b32_e32 v63, v2
	v_lshl_add_u64 v[64:65], s[30:31], 0, v[64:65]
	v_lshl_add_u64 v[66:67], v[58:59], 0, v[112:113]
	v_lshlrev_b64 v[58:59], 6, v[60:61]
	v_lshl_add_u64 v[62:63], v[64:65], 0, v[62:63]
	v_lshl_add_u64 v[58:59], s[66:67], 0, v[58:59]
	v_lshlrev_b64 v[62:63], 7, v[62:63]
	global_load_dword v103, v[58:59], off nt
	v_add_co_u32_e32 v58, vcc, s49, v58
	v_lshl_add_u64 v[56:57], v[56:57], 0, v[62:63]
	s_nop 0
	v_addc_co_u32_e32 v59, vcc, 0, v59, vcc
	global_load_dword v105, v[58:59], off nt
	s_nop 0
	global_load_dwordx4 v[58:61], v[54:55], off offset:16 nt
	global_load_dwordx4 v[70:73], v[54:55], off nt
	global_load_dwordx4 v[62:65], v[56:57], off offset:16 nt
	global_load_dwordx4 v[74:77], v[56:57], off nt
	s_nop 0
	global_load_dwordx4 v[54:57], v[66:67], off offset:16 nt
	s_nop 0
	global_load_dwordx4 v[66:69], v[66:67], off nt
	v_lshl_add_u64 v[114:115], s[68:69], 0, v[114:115]
	s_mov_b64 s[0:1], 0
	s_waitcnt vmcnt(8)
	v_max3_f32 v119, v118, v107, v109
	v_sub_f32_e32 v107, v107, v119
	v_exp_f32_e32 v121, v107
	v_sub_f32_e32 v107, v109, v119
	v_exp_f32_e32 v120, v107
	v_sub_f32_e32 v107, v118, v119
	v_lshlrev_b32_e32 v126, 16, v90
	v_and_b32_e32 v127, 0xffff0000, v90
	v_mul_f32_e32 v90, 0xbfb8aa3b, v126
	v_exp_f32_e32 v90, v90
	v_exp_f32_e32 v107, v107
	v_add_f32_e32 v109, v121, v120
	v_lshlrev_b32_e32 v124, 16, v94
	v_add_f32_e32 v90, 1.0, v90
	v_rcp_f32_e32 v128, v90
	v_mul_f32_e32 v90, 0xbfb8aa3b, v127
	v_exp_f32_e32 v90, v90
	v_add_f32_e32 v109, v107, v109
	v_rcp_f32_e32 v122, v109
	v_and_b32_e32 v125, 0xffff0000, v98
	v_add_f32_e32 v90, 1.0, v90
	v_rcp_f32_e32 v129, v90
	v_pk_mul_f32 v[120:121], v[120:121], v[122:123] op_sel_hi:[1,0]
	v_mul_f32_e32 v107, v107, v122
	v_lshlrev_b32_e32 v122, 16, v98
	v_and_b32_e32 v123, 0xffff0000, v94
	v_pk_mul_f32 v[124:125], v[120:121], v[124:125] op_sel:[1,0] op_sel_hi:[0,1]
	v_mul_f32_e32 v118, v108, v107
	v_pk_fma_f32 v[122:123], v[120:121], v[122:123], v[124:125]
	v_pk_mul_f32 v[126:127], v[128:129], v[126:127]
	v_pk_fma_f32 v[122:123], v[42:43], v[118:119], v[122:123] op_sel_hi:[1,0,1]
	v_lshlrev_b32_e32 v98, 16, v91
	v_pk_mul_f32 v[122:123], v[122:123], v[126:127]
	v_lshlrev_b32_e32 v94, 16, v95
	v_cvt_pk_bf16_f32 v90, v122, v123
	v_lshlrev_b32_e32 v122, 16, v99
	v_and_b32_e32 v123, 0xffff0000, v95
	v_and_b32_e32 v95, 0xffff0000, v99
	v_and_b32_e32 v99, 0xffff0000, v91
	v_mul_f32_e32 v91, 0xbfb8aa3b, v98
	v_exp_f32_e32 v91, v91
	v_pk_mul_f32 v[94:95], v[120:121], v[94:95] op_sel:[1,0] op_sel_hi:[0,1]
	v_pk_fma_f32 v[94:95], v[120:121], v[122:123], v[94:95]
	v_lshlrev_b32_e32 v122, 16, v92
	v_add_f32_e32 v91, 1.0, v91
	v_rcp_f32_e32 v124, v91
	v_mul_f32_e32 v91, 0xbfb8aa3b, v99
	v_exp_f32_e32 v91, v91
	v_and_b32_e32 v123, 0xffff0000, v92
	v_mul_f32_e32 v92, 0xbfb8aa3b, v122
	v_exp_f32_e32 v92, v92
	v_add_f32_e32 v91, 1.0, v91
	v_rcp_f32_e32 v125, v91
	v_pk_fma_f32 v[94:95], v[44:45], v[118:119], v[94:95] op_sel_hi:[1,0,1]
	v_add_f32_e32 v92, 1.0, v92
	v_pk_mul_f32 v[98:99], v[124:125], v[98:99]
	s_nop 0
	v_pk_mul_f32 v[94:95], v[94:95], v[98:99]
	v_lshlrev_b32_e32 v98, 16, v96
	v_and_b32_e32 v99, 0xffff0000, v100
	v_cvt_pk_bf16_f32 v91, v94, v95
	v_lshlrev_b32_e32 v94, 16, v100
	v_and_b32_e32 v95, 0xffff0000, v96
	v_pk_mul_f32 v[98:99], v[120:121], v[98:99] op_sel:[1,0] op_sel_hi:[0,1]
	v_pk_fma_f32 v[94:95], v[120:121], v[94:95], v[98:99]
	v_lshlrev_b32_e32 v98, 16, v93
	v_rcp_f32_e32 v124, v92
	v_mul_f32_e32 v92, 0xbfb8aa3b, v123
	v_and_b32_e32 v99, 0xffff0000, v93
	v_mul_f32_e32 v93, 0xbfb8aa3b, v98
	v_exp_f32_e32 v92, v92
	v_exp_f32_e32 v93, v93
	v_pk_fma_f32 v[94:95], v[38:39], v[118:119], v[94:95] op_sel_hi:[1,0,1]
	v_lshlrev_b32_e32 v96, 16, v97
	v_add_f32_e32 v92, 1.0, v92
	v_add_f32_e32 v93, 1.0, v93
	v_rcp_f32_e32 v125, v92
	v_rcp_f32_e32 v100, v93
	v_mul_f32_e32 v93, 0xbfb8aa3b, v99
	v_exp_f32_e32 v93, v93
	v_pk_mul_f32 v[122:123], v[124:125], v[122:123]
	v_add_f32_e32 v93, 1.0, v93
	v_pk_mul_f32 v[94:95], v[94:95], v[122:123]
	s_nop 0
	v_cvt_pk_bf16_f32 v92, v94, v95
	v_lshlrev_b32_e32 v94, 16, v101
	v_and_b32_e32 v95, 0xffff0000, v97
	v_and_b32_e32 v97, 0xffff0000, v101
	v_rcp_f32_e32 v101, v93
	v_pk_mul_f32 v[96:97], v[120:121], v[96:97] op_sel:[1,0] op_sel_hi:[0,1]
	v_pk_fma_f32 v[94:95], v[120:121], v[94:95], v[96:97]
	v_lshlrev_b32_e32 v96, 16, v82
	v_pk_mul_f32 v[98:99], v[100:101], v[98:99]
	v_pk_fma_f32 v[94:95], v[40:41], v[118:119], v[94:95] op_sel_hi:[1,0,1]
	v_and_b32_e32 v97, 0xffff0000, v86
	v_pk_mul_f32 v[94:95], v[94:95], v[98:99]
	v_lshlrev_b32_e32 v98, 16, v78
	v_and_b32_e32 v99, 0xffff0000, v78
	v_mul_f32_e32 v78, 0xbfb8aa3b, v98
	v_exp_f32_e32 v78, v78
	v_cvt_pk_bf16_f32 v93, v94, v95
	v_lshlrev_b32_e32 v94, 16, v86
	v_and_b32_e32 v95, 0xffff0000, v82
	v_add_f32_e32 v78, 1.0, v78
	v_rcp_f32_e32 v100, v78
	v_mul_f32_e32 v78, 0xbfb8aa3b, v99
	v_exp_f32_e32 v78, v78
	v_pk_mul_f32 v[96:97], v[120:121], v[96:97] op_sel:[1,0] op_sel_hi:[0,1]
	v_pk_fma_f32 v[94:95], v[120:121], v[94:95], v[96:97]
	v_lshlrev_b32_e32 v86, 16, v79
	v_add_f32_e32 v78, 1.0, v78
	v_rcp_f32_e32 v101, v78
	v_pk_fma_f32 v[94:95], v[34:35], v[118:119], v[94:95] op_sel_hi:[1,0,1]
	v_lshlrev_b32_e32 v82, 16, v83
	v_pk_mul_f32 v[98:99], v[100:101], v[98:99]
	s_nop 0
	v_pk_mul_f32 v[94:95], v[94:95], v[98:99]
	s_nop 0
	v_cvt_pk_bf16_f32 v78, v94, v95
	v_lshlrev_b32_e32 v94, 16, v87
	v_and_b32_e32 v95, 0xffff0000, v83
	v_and_b32_e32 v83, 0xffff0000, v87
	v_and_b32_e32 v87, 0xffff0000, v79
	v_mul_f32_e32 v79, 0xbfb8aa3b, v86
	v_exp_f32_e32 v79, v79
	v_pk_mul_f32 v[82:83], v[120:121], v[82:83] op_sel:[1,0] op_sel_hi:[0,1]
	v_pk_fma_f32 v[82:83], v[120:121], v[94:95], v[82:83]
	v_add_f32_e32 v79, 1.0, v79
	v_rcp_f32_e32 v96, v79
	v_mul_f32_e32 v79, 0xbfb8aa3b, v87
	v_exp_f32_e32 v79, v79
	v_pk_fma_f32 v[82:83], v[36:37], v[118:119], v[82:83] op_sel_hi:[1,0,1]
	v_add_f32_e32 v79, 1.0, v79
	v_rcp_f32_e32 v97, v79
	s_nop 0
	v_pk_mul_f32 v[86:87], v[96:97], v[86:87]
	s_nop 0
	v_pk_mul_f32 v[82:83], v[82:83], v[86:87]
	v_lshlrev_b32_e32 v86, 16, v85
	v_and_b32_e32 v87, 0xffff0000, v89
	v_cvt_pk_bf16_f32 v79, v82, v83
	v_lshlrev_b32_e32 v82, 16, v89
	v_and_b32_e32 v83, 0xffff0000, v85
	v_pk_mul_f32 v[86:87], v[120:121], v[86:87] op_sel:[1,0] op_sel_hi:[0,1]
	v_pk_fma_f32 v[82:83], v[120:121], v[82:83], v[86:87]
	v_lshlrev_b32_e32 v86, 16, v88
	v_and_b32_e32 v85, 0xffff0000, v88
	v_lshlrev_b32_e32 v88, 16, v80
	v_and_b32_e32 v89, 0xffff0000, v80
	v_mul_f32_e32 v80, 0xbfb8aa3b, v88
	v_exp_f32_e32 v80, v80
	v_and_b32_e32 v87, 0xffff0000, v84
	v_lshlrev_b32_e32 v84, 16, v84
	v_pk_mul_f32 v[84:85], v[120:121], v[84:85] op_sel:[1,0] op_sel_hi:[0,1]
	v_add_f32_e32 v80, 1.0, v80
	v_rcp_f32_e32 v94, v80
	v_mul_f32_e32 v80, 0xbfb8aa3b, v89
	v_exp_f32_e32 v80, v80
	v_pk_fma_f32 v[84:85], v[120:121], v[86:87], v[84:85]
	v_pk_fma_f32 v[82:83], v[32:33], v[118:119], v[82:83] op_sel_hi:[1,0,1]
	v_pk_fma_f32 v[84:85], v[30:31], v[118:119], v[84:85] op_sel_hi:[1,0,1]
	v_add_f32_e32 v80, 1.0, v80
	v_rcp_f32_e32 v95, v80
	s_nop 0
	v_pk_mul_f32 v[88:89], v[94:95], v[88:89]
	s_nop 0
	v_pk_mul_f32 v[84:85], v[84:85], v[88:89]
	s_nop 0
	v_cvt_pk_bf16_f32 v80, v84, v85
	v_lshlrev_b32_e32 v84, 16, v81
	v_and_b32_e32 v85, 0xffff0000, v81
	v_mul_f32_e32 v81, 0xbfb8aa3b, v84
	v_exp_f32_e32 v81, v81
	s_nop 0
	v_add_f32_e32 v81, 1.0, v81
	v_rcp_f32_e32 v86, v81
	v_mul_f32_e32 v81, 0xbfb8aa3b, v85
	v_exp_f32_e32 v81, v81
	s_nop 0
	v_add_f32_e32 v81, 1.0, v81
	v_rcp_f32_e32 v87, v81
	s_nop 0
	v_pk_mul_f32 v[84:85], v[86:87], v[84:85]
	s_nop 0
	v_pk_mul_f32 v[82:83], v[82:83], v[84:85]
	s_waitcnt vmcnt(0)
	v_lshlrev_b32_e32 v86, 16, v66
	v_cvt_pk_bf16_f32 v81, v82, v83
	v_lshl_add_u64 v[82:83], v[114:115], 0, v[116:117]
	global_store_dwordx4 v[82:83], v[90:93], off
	global_store_dwordx4 v[82:83], v[78:81], off offset:16
	v_and_b32_e32 v87, 0xffff0000, v66
	v_mul_f32_e32 v66, 0xbfb8aa3b, v86
	v_log_f32_e32 v78, v46
	v_exp_f32_e32 v66, v66
	v_lshlrev_b32_e32 v84, 16, v70
	v_and_b32_e32 v85, 0xffff0000, v74
	v_add_f32_e32 v78, v4, v78
	v_max3_f32 v79, v78, v103, v105
	v_sub_f32_e32 v80, v103, v79
	v_exp_f32_e32 v81, v80
	v_sub_f32_e32 v80, v105, v79
	v_exp_f32_e32 v80, v80
	v_sub_f32_e32 v78, v78, v79
	v_exp_f32_e32 v78, v78
	v_add_f32_e32 v66, 1.0, v66
	v_rcp_f32_e32 v88, v66
	v_mul_f32_e32 v66, 0xbfb8aa3b, v87
	v_add_f32_e32 v79, v81, v80
	v_exp_f32_e32 v66, v66
	v_add_f32_e32 v79, v78, v79
	v_rcp_f32_e32 v82, v79
	v_add_f32_e32 v66, 1.0, v66
	v_rcp_f32_e32 v89, v66
	v_pk_mul_f32 v[80:81], v[80:81], v[82:83] op_sel_hi:[1,0]
	v_mul_f32_e32 v78, v78, v82
	v_lshlrev_b32_e32 v82, 16, v74
	v_and_b32_e32 v83, 0xffff0000, v70
	v_pk_mul_f32 v[84:85], v[80:81], v[84:85] op_sel:[1,0] op_sel_hi:[0,1]
	v_mul_f32_e32 v78, v104, v78
	v_pk_fma_f32 v[82:83], v[80:81], v[82:83], v[84:85]
	v_pk_mul_f32 v[86:87], v[88:89], v[86:87]
	v_pk_fma_f32 v[82:83], v[26:27], v[78:79], v[82:83] op_sel_hi:[1,0,1]
	v_lshlrev_b32_e32 v74, 16, v67
	v_pk_mul_f32 v[82:83], v[82:83], v[86:87]
	v_lshlrev_b32_e32 v70, 16, v71
	v_cvt_pk_bf16_f32 v66, v82, v83
	v_lshlrev_b32_e32 v82, 16, v75
	v_and_b32_e32 v83, 0xffff0000, v71
	v_and_b32_e32 v71, 0xffff0000, v75
	v_and_b32_e32 v75, 0xffff0000, v67
	v_mul_f32_e32 v67, 0xbfb8aa3b, v74
	v_exp_f32_e32 v67, v67
	v_pk_mul_f32 v[70:71], v[80:81], v[70:71] op_sel:[1,0] op_sel_hi:[0,1]
	v_pk_fma_f32 v[70:71], v[80:81], v[82:83], v[70:71]
	v_lshlrev_b32_e32 v82, 16, v68
	v_add_f32_e32 v67, 1.0, v67
	v_rcp_f32_e32 v84, v67
	v_mul_f32_e32 v67, 0xbfb8aa3b, v75
	v_exp_f32_e32 v67, v67
	v_and_b32_e32 v83, 0xffff0000, v68
	v_mul_f32_e32 v68, 0xbfb8aa3b, v82
	v_exp_f32_e32 v68, v68
	v_add_f32_e32 v67, 1.0, v67
	v_rcp_f32_e32 v85, v67
	v_pk_fma_f32 v[70:71], v[28:29], v[78:79], v[70:71] op_sel_hi:[1,0,1]
	v_add_f32_e32 v68, 1.0, v68
	v_pk_mul_f32 v[74:75], v[84:85], v[74:75]
	s_nop 0
	v_pk_mul_f32 v[70:71], v[70:71], v[74:75]
	v_lshlrev_b32_e32 v74, 16, v72
	v_and_b32_e32 v75, 0xffff0000, v76
	v_cvt_pk_bf16_f32 v67, v70, v71
	v_lshlrev_b32_e32 v70, 16, v76
	v_and_b32_e32 v71, 0xffff0000, v72
	v_pk_mul_f32 v[74:75], v[80:81], v[74:75] op_sel:[1,0] op_sel_hi:[0,1]
	v_pk_fma_f32 v[70:71], v[80:81], v[70:71], v[74:75]
	v_lshlrev_b32_e32 v74, 16, v69
	v_rcp_f32_e32 v84, v68
	v_mul_f32_e32 v68, 0xbfb8aa3b, v83
	v_and_b32_e32 v75, 0xffff0000, v69
	v_mul_f32_e32 v69, 0xbfb8aa3b, v74
	v_exp_f32_e32 v68, v68
	v_exp_f32_e32 v69, v69
	v_pk_fma_f32 v[70:71], v[22:23], v[78:79], v[70:71] op_sel_hi:[1,0,1]
	v_lshlrev_b32_e32 v72, 16, v73
	v_add_f32_e32 v68, 1.0, v68
	v_add_f32_e32 v69, 1.0, v69
	v_rcp_f32_e32 v85, v68
	v_rcp_f32_e32 v76, v69
	v_mul_f32_e32 v69, 0xbfb8aa3b, v75
	v_exp_f32_e32 v69, v69
	v_pk_mul_f32 v[82:83], v[84:85], v[82:83]
	v_add_f32_e32 v69, 1.0, v69
	v_pk_mul_f32 v[70:71], v[70:71], v[82:83]
	s_nop 0
	v_cvt_pk_bf16_f32 v68, v70, v71
	v_lshlrev_b32_e32 v70, 16, v77
	v_and_b32_e32 v71, 0xffff0000, v73
	v_and_b32_e32 v73, 0xffff0000, v77
	v_rcp_f32_e32 v77, v69
	v_pk_mul_f32 v[72:73], v[80:81], v[72:73] op_sel:[1,0] op_sel_hi:[0,1]
	v_pk_fma_f32 v[70:71], v[80:81], v[70:71], v[72:73]
	v_lshlrev_b32_e32 v72, 16, v58
	v_pk_mul_f32 v[74:75], v[76:77], v[74:75]
	v_pk_fma_f32 v[70:71], v[24:25], v[78:79], v[70:71] op_sel_hi:[1,0,1]
	v_and_b32_e32 v73, 0xffff0000, v62
	v_pk_mul_f32 v[70:71], v[70:71], v[74:75]
	v_lshlrev_b32_e32 v74, 16, v54
	v_and_b32_e32 v75, 0xffff0000, v54
	v_mul_f32_e32 v54, 0xbfb8aa3b, v74
	v_exp_f32_e32 v54, v54
	v_cvt_pk_bf16_f32 v69, v70, v71
	v_lshlrev_b32_e32 v70, 16, v62
	v_and_b32_e32 v71, 0xffff0000, v58
	v_add_f32_e32 v54, 1.0, v54
	v_rcp_f32_e32 v76, v54
	v_mul_f32_e32 v54, 0xbfb8aa3b, v75
	v_exp_f32_e32 v54, v54
	v_pk_mul_f32 v[72:73], v[80:81], v[72:73] op_sel:[1,0] op_sel_hi:[0,1]
	v_pk_fma_f32 v[70:71], v[80:81], v[70:71], v[72:73]
	v_lshlrev_b32_e32 v62, 16, v55
	v_add_f32_e32 v54, 1.0, v54
	v_rcp_f32_e32 v77, v54
	v_pk_fma_f32 v[70:71], v[18:19], v[78:79], v[70:71] op_sel_hi:[1,0,1]
	v_lshlrev_b32_e32 v58, 16, v59
	v_pk_mul_f32 v[74:75], v[76:77], v[74:75]
	s_nop 0
	v_pk_mul_f32 v[70:71], v[70:71], v[74:75]
	s_nop 0
	v_cvt_pk_bf16_f32 v54, v70, v71
	v_lshlrev_b32_e32 v70, 16, v63
	v_and_b32_e32 v71, 0xffff0000, v59
	v_and_b32_e32 v59, 0xffff0000, v63
	v_and_b32_e32 v63, 0xffff0000, v55
	v_mul_f32_e32 v55, 0xbfb8aa3b, v62
	v_exp_f32_e32 v55, v55
	v_pk_mul_f32 v[58:59], v[80:81], v[58:59] op_sel:[1,0] op_sel_hi:[0,1]
	v_pk_fma_f32 v[58:59], v[80:81], v[70:71], v[58:59]
	v_add_f32_e32 v55, 1.0, v55
	v_rcp_f32_e32 v72, v55
	v_mul_f32_e32 v55, 0xbfb8aa3b, v63
	v_exp_f32_e32 v55, v55
	v_pk_fma_f32 v[58:59], v[20:21], v[78:79], v[58:59] op_sel_hi:[1,0,1]
	v_add_f32_e32 v55, 1.0, v55
	v_rcp_f32_e32 v73, v55
	s_nop 0
	v_pk_mul_f32 v[62:63], v[72:73], v[62:63]
	s_nop 0
	v_pk_mul_f32 v[58:59], v[58:59], v[62:63]
	v_lshlrev_b32_e32 v62, 16, v61
	v_and_b32_e32 v63, 0xffff0000, v65
	v_cvt_pk_bf16_f32 v55, v58, v59
	v_lshlrev_b32_e32 v58, 16, v65
	v_and_b32_e32 v59, 0xffff0000, v61
	v_pk_mul_f32 v[62:63], v[80:81], v[62:63] op_sel:[1,0] op_sel_hi:[0,1]
	v_pk_fma_f32 v[58:59], v[80:81], v[58:59], v[62:63]
	v_lshlrev_b32_e32 v62, 16, v64
	v_and_b32_e32 v61, 0xffff0000, v64
	v_lshlrev_b32_e32 v64, 16, v56
	v_and_b32_e32 v65, 0xffff0000, v56
	v_mul_f32_e32 v56, 0xbfb8aa3b, v64
	v_exp_f32_e32 v56, v56
	v_and_b32_e32 v63, 0xffff0000, v60
	v_lshlrev_b32_e32 v60, 16, v60
	v_pk_mul_f32 v[60:61], v[80:81], v[60:61] op_sel:[1,0] op_sel_hi:[0,1]
	v_add_f32_e32 v56, 1.0, v56
	v_rcp_f32_e32 v70, v56
	v_mul_f32_e32 v56, 0xbfb8aa3b, v65
	v_exp_f32_e32 v56, v56
	v_pk_fma_f32 v[60:61], v[80:81], v[62:63], v[60:61]
	v_pk_fma_f32 v[58:59], v[16:17], v[78:79], v[58:59] op_sel_hi:[1,0,1]
	v_pk_fma_f32 v[60:61], v[14:15], v[78:79], v[60:61] op_sel_hi:[1,0,1]
	v_add_f32_e32 v56, 1.0, v56
	v_rcp_f32_e32 v71, v56
	s_nop 0
	v_pk_mul_f32 v[64:65], v[70:71], v[64:65]
	s_nop 0
	v_pk_mul_f32 v[60:61], v[60:61], v[64:65]
	s_nop 0
	v_cvt_pk_bf16_f32 v56, v60, v61
	v_lshlrev_b32_e32 v60, 16, v57
	v_and_b32_e32 v61, 0xffff0000, v57
	v_mul_f32_e32 v57, 0xbfb8aa3b, v60
	v_exp_f32_e32 v57, v57
	s_nop 0
	v_add_f32_e32 v57, 1.0, v57
	v_rcp_f32_e32 v62, v57
	v_mul_f32_e32 v57, 0xbfb8aa3b, v61
	v_exp_f32_e32 v57, v57
	s_nop 0
	v_add_f32_e32 v57, 1.0, v57
	v_rcp_f32_e32 v63, v57
	s_nop 0
	v_pk_mul_f32 v[60:61], v[62:63], v[60:61]
	s_nop 0
	v_pk_mul_f32 v[58:59], v[58:59], v[60:61]
	s_nop 0
	v_cvt_pk_bf16_f32 v57, v58, v59
	v_lshl_add_u64 v[58:59], v[114:115], 0, v[112:113]
	global_store_dwordx4 v[58:59], v[66:69], off
	global_store_dwordx4 v[58:59], v[54:57], off offset:16
